# v94 + V-transpose GEMM epilogue: 16-byte stores via v_permlane16_swap quad exchange, saddr addressing (16 dwordx4 instead of 32 dwordx2 per wave)
# speedup vs baseline: 1.0146x; 1.0067x over previous
.LBB0_492:
	s_lshl_b32 s43, s50, 8
	s_add_i32 s43, s43, s69
	s_lshr_b32 s50, s43, 4
	s_and_b32 s50, s50, 0x7ffffc0
	s_lshl_b32 s45, s77, 8
	s_add_i32 s50, s50, s77
	s_and_b32 s45, s45, 0x700
	s_and_b32 s50, s50, 0x7fffff8
	s_bfe_u32 s51, s43, 0x30007
	s_or_b32 s45, s45, s70
	s_or_b32 s50, s50, s51
	s_lshl_b32 s54, s50, 5
	s_lshr_b32 s45, s45, 6
	s_or_b32 s50, s54, s45
	s_ashr_i32 s51, s50, 31
	s_lshl_b64 s[50:51], s[50:51], 14
	s_add_u32 s50, s81, s50
	s_addc_u32 s51, s82, s51
	s_or_b32 s56, s45, 2
	s_or_b32 s54, s54, s56
	s_ashr_i32 s55, s54, 31
	s_lshl_b64 s[54:55], s[54:55], 14
	s_add_u32 s54, s81, s54
	s_addc_u32 s55, s82, s55
	v_lshl_add_u32 v160, v148, 1, v136
	v_add_u32_e32 v160, v160, v146
	v_add_u32_e32 v161, 0x1000, v160
	v_cvt_pk_bf16_f32 v124, v124, v125
	v_cvt_pk_bf16_f32 v125, v126, v127
	v_cvt_pk_bf16_f32 v126, v120, v121
	v_cvt_pk_bf16_f32 v127, v122, v123
	s_nop 1
	v_permlane16_swap_b32_e32 v124, v126
	v_permlane16_swap_b32_e32 v125, v127
	global_store_dwordx4 v160, v[124:127], s[50:51]
	v_cvt_pk_bf16_f32 v112, v112, v113
	v_cvt_pk_bf16_f32 v113, v114, v115
	v_cvt_pk_bf16_f32 v114, v104, v105
	v_cvt_pk_bf16_f32 v115, v106, v107
	s_nop 1
	v_permlane16_swap_b32_e32 v112, v114
	v_permlane16_swap_b32_e32 v113, v115
	global_store_dwordx4 v160, v[112:115], s[54:55]
	v_cvt_pk_bf16_f32 v116, v116, v117
	v_cvt_pk_bf16_f32 v117, v118, v119
	v_cvt_pk_bf16_f32 v118, v108, v109
	v_cvt_pk_bf16_f32 v119, v110, v111
	s_nop 1
	v_permlane16_swap_b32_e32 v116, v118
	v_permlane16_swap_b32_e32 v117, v119
	global_store_dwordx4 v160, v[116:119], s[50:51] offset:2048
	v_cvt_pk_bf16_f32 v96, v96, v97
	v_cvt_pk_bf16_f32 v97, v98, v99
	v_cvt_pk_bf16_f32 v98, v88, v89
	v_cvt_pk_bf16_f32 v99, v90, v91
	s_nop 1
	v_permlane16_swap_b32_e32 v96, v98
	v_permlane16_swap_b32_e32 v97, v99
	global_store_dwordx4 v160, v[96:99], s[54:55] offset:2048
	v_cvt_pk_bf16_f32 v100, v100, v101
	v_cvt_pk_bf16_f32 v101, v102, v103
	v_cvt_pk_bf16_f32 v102, v92, v93
	v_cvt_pk_bf16_f32 v103, v94, v95
	s_nop 1
	v_permlane16_swap_b32_e32 v100, v102
	v_permlane16_swap_b32_e32 v101, v103
	global_store_dwordx4 v161, v[100:103], s[50:51]
	v_cvt_pk_bf16_f32 v80, v80, v81
	v_cvt_pk_bf16_f32 v81, v82, v83
	v_cvt_pk_bf16_f32 v82, v72, v73
	v_cvt_pk_bf16_f32 v83, v74, v75
	s_nop 1
	v_permlane16_swap_b32_e32 v80, v82
	v_permlane16_swap_b32_e32 v81, v83
	global_store_dwordx4 v161, v[80:83], s[54:55]
	v_cvt_pk_bf16_f32 v84, v84, v85
	v_cvt_pk_bf16_f32 v85, v86, v87
	v_cvt_pk_bf16_f32 v86, v76, v77
	v_cvt_pk_bf16_f32 v87, v78, v79
	s_nop 1
	v_permlane16_swap_b32_e32 v84, v86
	v_permlane16_swap_b32_e32 v85, v87
	global_store_dwordx4 v161, v[84:87], s[50:51] offset:2048
	v_cvt_pk_bf16_f32 v68, v68, v69
	v_cvt_pk_bf16_f32 v69, v70, v71
	v_cvt_pk_bf16_f32 v70, v64, v65
	v_cvt_pk_bf16_f32 v71, v66, v67
	s_nop 1
	v_permlane16_swap_b32_e32 v68, v70
	v_permlane16_swap_b32_e32 v69, v71
	global_store_dwordx4 v161, v[68:71], s[54:55] offset:2048
	s_addk_i32 s43, 0x80
	s_lshr_b32 s50, s43, 4
	s_and_b32 s50, s50, 0x7ffffc0
	s_add_i32 s50, s50, s77
	s_and_b32 s50, s50, 0x7fffff8
	s_bfe_u32 s43, s43, 0x30007
	s_or_b32 s43, s50, s43
	s_lshl_b32 s43, s43, 5
	s_or_b32 s50, s43, s45
	s_ashr_i32 s51, s50, 31
	s_lshl_b64 s[50:51], s[50:51], 14
	s_add_u32 s50, s81, s50
	s_addc_u32 s51, s82, s51
	s_or_b32 s54, s43, s56
	s_ashr_i32 s55, s54, 31
	s_lshl_b64 s[54:55], s[54:55], 14
	s_add_u32 s54, s81, s54
	s_addc_u32 s55, s82, s55
	v_cvt_pk_bf16_f32 v60, v60, v61
	v_cvt_pk_bf16_f32 v61, v62, v63
	v_cvt_pk_bf16_f32 v62, v56, v57
	v_cvt_pk_bf16_f32 v63, v58, v59
	s_nop 1
	v_permlane16_swap_b32_e32 v60, v62
	v_permlane16_swap_b32_e32 v61, v63
	global_store_dwordx4 v160, v[60:63], s[50:51]
	v_cvt_pk_bf16_f32 v48, v48, v49
	v_cvt_pk_bf16_f32 v49, v50, v51
	v_cvt_pk_bf16_f32 v50, v40, v41
	v_cvt_pk_bf16_f32 v51, v42, v43
	s_nop 1
	v_permlane16_swap_b32_e32 v48, v50
	v_permlane16_swap_b32_e32 v49, v51
	global_store_dwordx4 v160, v[48:51], s[54:55]
	v_cvt_pk_bf16_f32 v52, v52, v53
	v_cvt_pk_bf16_f32 v53, v54, v55
	v_cvt_pk_bf16_f32 v54, v44, v45
	v_cvt_pk_bf16_f32 v55, v46, v47
	s_nop 1
	v_permlane16_swap_b32_e32 v52, v54
	v_permlane16_swap_b32_e32 v53, v55
	global_store_dwordx4 v160, v[52:55], s[50:51] offset:2048
	v_cvt_pk_bf16_f32 v32, v32, v33
	v_cvt_pk_bf16_f32 v33, v34, v35
	v_cvt_pk_bf16_f32 v34, v24, v25
	v_cvt_pk_bf16_f32 v35, v26, v27
	s_nop 1
	v_permlane16_swap_b32_e32 v32, v34
	v_permlane16_swap_b32_e32 v33, v35
	global_store_dwordx4 v160, v[32:35], s[54:55] offset:2048
	v_cvt_pk_bf16_f32 v36, v36, v37
	v_cvt_pk_bf16_f32 v37, v38, v39
	v_cvt_pk_bf16_f32 v38, v28, v29
	v_cvt_pk_bf16_f32 v39, v30, v31
	s_nop 1
	v_permlane16_swap_b32_e32 v36, v38
	v_permlane16_swap_b32_e32 v37, v39
	global_store_dwordx4 v161, v[36:39], s[50:51]
	v_cvt_pk_bf16_f32 v16, v16, v17
	v_cvt_pk_bf16_f32 v17, v18, v19
	v_cvt_pk_bf16_f32 v18, v8, v9
	v_cvt_pk_bf16_f32 v19, v10, v11
	s_nop 1
	v_permlane16_swap_b32_e32 v16, v18
	v_permlane16_swap_b32_e32 v17, v19
	global_store_dwordx4 v161, v[16:19], s[54:55]
	v_cvt_pk_bf16_f32 v20, v20, v21
	v_cvt_pk_bf16_f32 v21, v22, v23
	v_cvt_pk_bf16_f32 v22, v12, v13
	v_cvt_pk_bf16_f32 v23, v14, v15
	s_nop 1
	v_permlane16_swap_b32_e32 v20, v22
	v_permlane16_swap_b32_e32 v21, v23
	global_store_dwordx4 v161, v[20:23], s[50:51] offset:2048
	v_cvt_pk_bf16_f32 v4, v4, v5
	v_cvt_pk_bf16_f32 v5, v6, v7
	v_cvt_pk_bf16_f32 v6, v0, v1
	v_cvt_pk_bf16_f32 v7, v2, v3
	s_nop 1
	v_permlane16_swap_b32_e32 v4, v6
	v_permlane16_swap_b32_e32 v5, v7
	global_store_dwordx4 v161, v[4:7], s[54:55] offset:2048
	s_andn2_b64 vcc, exec, s[4:5]
	s_mov_b64 s[4:5], -1
	s_cbranch_vccnz .LBB0_481
	s_andn2_b64 vcc, exec, s[6:7]
	s_cbranch_vccnz .LBB0_480
	s_barrier
	s_branch .LBB0_480
